# attention phase: units handed to the 8 waves of a workgroup through an LDS ticket counter (dynamic instead of 4 fixed units per wave)
# speedup vs baseline: 1.0094x; 1.0094x over previous
; __device__ void phase_attn(const P& p) {
;   int wid = __builtin_amdgcn_readfirstlane(opaque_tid(p) >> 6);
;   for (int u = blockIdx.x * 8 + wid; u < 32768 / ATT_NT; u += gridDim.x * 8) attn_unitN<ATT_NT>(p, u);
.LBB0_229:
	v_mbcnt_lo_u32_b32 v0, -1, 0
	v_mbcnt_hi_u32_b32 v0, -1, v0
	s_lshl_b32 s1, s2, 3
	v_add_u32_e32 v0, s33, v0
	s_nop 0
	v_readfirstlane_b32 s0, v0
	s_ashr_i32 s0, s0, 6
	v_mov_b32_e32 v245, 0x20010
	s_cmp_lg_u32 s0, 0
	s_cbranch_scc1 .Lmy_at_nz
	v_mov_b32_e32 v244, 0
	ds_write_b32 v245, v244
.Lmy_at_nz:
	s_waitcnt lgkmcnt(0)
	s_barrier
	v_mov_b32_e32 v245, 0x20010
	v_mov_b32_e32 v244, 1
	s_mov_b64 s[98:99], exec
	s_mov_b64 exec, 1
	ds_add_rtn_u32 v243, v245, v244
	s_waitcnt lgkmcnt(0)
	s_mov_b64 exec, s[98:99]
	s_nop 1
	v_readfirstlane_b32 s3, v243
	s_lshl_b32 s100, s2, 3
	s_and_b32 s101, s3, 7
	s_lshr_b32 s3, s3, 3
	s_lshl_b32 s3, s3, 11
	s_add_i32 s3, s3, s101
	s_add_i32 s3, s3, s100
	s_cmpk_gt_i32 s3, 0x1fff
	s_cbranch_scc1 .LBB0_269
	s_add_u32 s26, s50, 0x8000000
	s_addc_u32 s27, s51, 0
	s_add_u32 s28, s50, 0xc000000
	v_mbcnt_lo_u32_b32 v0, -1, 0
	s_addc_u32 s29, s51, 0
	s_lshl_b32 s30, s70, 3
	s_movk_i32 s31, 0xf000
	s_movk_i32 s40, 0xff
	s_mov_b32 s9, 0
	v_mov_b32_e32 v145, 0
	s_mov_b32 s41, 0xf149f2ca
	v_mbcnt_hi_u32_b32 v199, -1, v0
	v_mov_b32_e32 v219, 0xff800000

; __device__ __forceinline__ void attn_step(int ks, const KVB& b, int L16, int r, int i0, int iq, int lane,
;                                           const bf16x8* qs, f32x4 (&o)[4], float& mrun, float& lrun) {
;   asm volatile("" : "+v"(lane), "+v"(iq));
;   asm volatile("" : "+s"(r), "+s"(i0));
;   const int quad = lane >> 4;
;   bf16x8 qB0 = qs[0], qB1 = qs[64];
;   int cV, sV; attn_desc(ks, quad, r, i0, cV, sV);
;   int D = ks < 12 ? 4 : (ks < 18 ? 16 : 64);
;   f32x4 z = {0.f, 0.f, 0.f, 0.f};
;   f32x4 sa = __builtin_amdgcn_mfma_f32_16x16x32_bf16(b.k0, qB0, z, 0, 0, 0);
;   sa = __builtin_amdgcn_mfma_f32_16x16x32_bf16(b.k1, qB1, sa, 0, 0, 0);
;   f32x4 sb = __builtin_amdgcn_mfma_f32_16x16x32_bf16(b.k2, qB0, z, 0, 0, 0);
;   sb = __builtin_amdgcn_mfma_f32_16x16x32_bf16(b.k3, qB1, sb, 0, 0, 0);
;   int jlo = max(iq - D + (cV < r ? 1 : 0), 0) - sV;
;   int jhi = min(iq + D - (cV > r ? 1 : 0), L16 - 1) - sV;
;   const float NINF = -__builtin_inff();
;   float s8[8];
;   float mt = -1e30f;
; #pragma unroll
;   for (int j = 0; j < 8; ++j) {
;     float sv = j < 4 ? sa[j] : sb[j - 4];
;     sv = (j >= jlo && j <= jhi) ? sv : NINF;
;     s8[j] = sv;
;     mt = fmaxf(mt, sv);
;   }
;   mt = fmaxf(mt, __shfl_xor(mt, 16));
;   mt = fmaxf(mt, __shfl_xor(mt, 32));
;   float mnew = fmaxf(mrun, mt);
;   float alpha = __builtin_amdgcn_exp2f(mrun - mnew);
;   mrun = mnew;
;   float ps = 0.f;
;   float p8[8];
; #pragma unroll
;   for (int j = 0; j < 8; ++j) { p8[j] = __builtin_amdgcn_exp2f(s8[j] - mnew); ps += p8[j]; }
;   lrun = lrun * alpha + ps;
;   union { uint4 u; bf16x8 v; } pb;
;   pb.u = make_uint4(pack2(p8[0], p8[1]), pack2(p8[2], p8[3]), pack2(p8[4], p8[5]), pack2(p8[6], p8[7]));
; #pragma unroll
;   for (int dt = 0; dt < 4; ++dt) { o[dt][0] *= alpha; o[dt][1] *= alpha; o[dt][2] *= alpha; o[dt][3] *= alpha; }
;   o[0] = __builtin_amdgcn_mfma_f32_16x16x32_bf16(b.v0, pb.v, o[0], 0, 0, 0);
;   o[1] = __builtin_amdgcn_mfma_f32_16x16x32_bf16(b.v1, pb.v, o[1], 0, 0, 0);
;   o[2] = __builtin_amdgcn_mfma_f32_16x16x32_bf16(b.v2, pb.v, o[2], 0, 0, 0);
;   o[3] = __builtin_amdgcn_mfma_f32_16x16x32_bf16(b.v3, pb.v, o[3], 0, 0, 0);
; }
; template <int NT>
; __device__ void attn_unitN(const P& p, int u) {
;     ...
;   for (int kk = 0; kk < 5; ++kk) {
;     int e0 = 18 + NT * kk, ks = 18 + kk;
; #pragma unroll
;     for (int t = 0; t < NT; t += 2) {
.LBB0_267:
	s_mov_b32 s0, s42
	s_mov_b32 s1, s46
	ds_read_b128 v[128:131], v228
	ds_read_b128 v[132:135], v228 offset:1024
	s_waitcnt vmcnt(21) lgkmcnt(1)
	v_mfma_f32_16x16x32_bf16 v[116:119], v[116:119], v[128:131], 0
	s_sub_i32 s0, s1, 64
	v_add_u32_e32 v136, s11, v246
	v_mfma_f32_16x16x32_bf16 v[124:127], v[124:127], v[128:131], 0
	v_lshl_add_u32 v136, v136, 3, s0
	v_ashrrev_i32_e32 v192, 2, v180
	v_ashrrev_i32_e32 v193, 31, v192
	s_waitcnt vmcnt(20) lgkmcnt(0)
	v_mfma_f32_16x16x32_bf16 v[112:115], v[112:115], v[132:135], v[116:119]
	v_lshl_add_u64 v[128:129], s[4:5], 0, v[192:193]
	v_lshlrev_b64 v[128:129], 9, v[128:129]
	s_nop 0
	v_subrev_u32_e32 v116, 64, v225
	v_add_u32_e32 v117, 64, v225
	v_mfma_f32_16x16x32_bf16 v[120:123], v[120:123], v[132:135], v[124:127]
	v_max_i32_e32 v116, 0, v116
	v_min_i32_e32 v117, s43, v117
	v_sub_u32_e32 v116, v116, v136
	v_sub_u32_e32 v117, v117, v136
	v_cmp_lt_i32_e32 vcc, 0, v116
	v_cmp_gt_i32_e64 s[0:1], 0, v117
	s_or_b64 vcc, vcc, s[0:1]
	s_nop 0
	v_cndmask_b32_e32 v118, v120, v219, vcc
	v_cmp_lt_i32_e32 vcc, 1, v116
	v_cmp_gt_i32_e64 s[0:1], 1, v117
	s_or_b64 vcc, vcc, s[0:1]
	v_cndmask_b32_e32 v119, v121, v219, vcc
	v_cmp_lt_i32_e32 vcc, 2, v116
	v_cmp_gt_i32_e64 s[0:1], 2, v117
	s_or_b64 vcc, vcc, s[0:1]
	v_cndmask_b32_e32 v121, v122, v219, vcc
	v_cmp_lt_i32_e32 vcc, 3, v116
	v_cmp_gt_i32_e64 s[0:1], 3, v117
	s_or_b64 vcc, vcc, s[0:1]
	v_cndmask_b32_e32 v122, v123, v219, vcc
	v_cmp_lt_i32_e32 vcc, 4, v116
	v_cmp_gt_i32_e64 s[0:1], 4, v117
	s_or_b64 vcc, vcc, s[0:1]
	v_cndmask_b32_e32 v112, v112, v219, vcc
	v_cmp_lt_i32_e32 vcc, 5, v116
	v_cmp_gt_i32_e64 s[0:1], 5, v117
	s_or_b64 vcc, vcc, s[0:1]
	v_cndmask_b32_e32 v113, v113, v219, vcc
	v_cmp_lt_i32_e32 vcc, 6, v116
	v_cmp_gt_i32_e64 s[0:1], 6, v117
	s_or_b64 vcc, vcc, s[0:1]
	v_max3_f32 v120, v118, s41, v119
	v_cndmask_b32_e32 v114, v114, v219, vcc
	v_cmp_lt_i32_e32 vcc, 7, v116
	v_cmp_gt_i32_e64 s[0:1], 7, v117
	v_max3_f32 v120, v120, v121, v122
	s_or_b64 vcc, vcc, s[0:1]
	v_max3_f32 v120, v120, v112, v113
	v_cndmask_b32_e32 v115, v115, v219, vcc
	v_max3_f32 v116, v120, v114, v115
	v_mov_b32_e32 v117, v116
	s_nop 1
	v_permlane16_swap_b32_e32 v116, v117
	s_mov_b32 s0, s56
	s_mov_b32 s1, s46
	s_add_i32 s22, s11, 20
	v_add_u32_e32 v180, 32, v180
	s_waitcnt lgkmcnt(0)
	v_max_f32_e32 v116, v116, v117
	v_mov_b32_e32 v117, v116
	s_nop 1
	v_permlane32_swap_b32_e32 v116, v117
	s_waitcnt lgkmcnt(0)
	v_max3_f32 v182, v143, v116, v117
	v_sub_f32_e32 v112, v112, v182
	v_exp_f32_e32 v171, v112
	v_sub_f32_e32 v112, v113, v182
	v_exp_f32_e32 v173, v112
	v_sub_f32_e32 v112, v114, v182
	v_exp_f32_e32 v175, v112
	v_sub_f32_e32 v112, v115, v182
	v_exp_f32_e32 v177, v112
	v_max_i32_e32 v112, 0, v181
	v_max_i32_e32 v113, -4, v181
	v_sub_f32_e32 v117, v118, v182
	v_min_i32_e32 v112, s43, v112
	v_add_u32_e32 v113, 4, v113
	v_exp_f32_e32 v163, v117
	v_sub_f32_e32 v117, v119, v182
	v_min_u32_e32 v114, s43, v113
	v_lshlrev_b32_e32 v194, 4, v112
	v_exp_f32_e32 v165, v117
	v_sub_f32_e32 v117, v121, v182
	v_add_u32_e32 v144, s8, v194
	v_lshlrev_b32_e32 v195, 4, v114
	v_sub_f32_e32 v116, v143, v182
	v_exp_f32_e32 v167, v117
	v_sub_f32_e32 v117, v122, v182
	v_lshrrev_b32_e32 v243, 8, v144
	v_and_b32_e32 v244, 15, v144
	v_lshlrev_b32_e32 v243, 18, v243
	v_lshl_or_b32 v243, v244, 11, v243
	v_bfe_u32 v244, v144, 6, 2
	v_lshl_or_b32 v243, v244, 9, v243
	v_bfe_u32 v244, v144, 4, 2
	v_lshl_or_b32 v112, v244, 5, v243
	v_mov_b32_e32 v113, 0
	v_add_u32_e32 v144, s8, v195
	v_exp_f32_e32 v169, v117
	v_exp_f32_e32 v179, v116
	v_lshl_add_u64 v[116:117], v[154:155], 0, v[112:113]
	v_lshrrev_b32_e32 v243, 8, v144
	v_and_b32_e32 v244, 15, v144
	v_lshlrev_b32_e32 v243, 18, v243
	v_lshl_or_b32 v243, v244, 11, v243
	v_bfe_u32 v244, v144, 6, 2
	v_lshl_or_b32 v243, v244, 9, v243
	v_bfe_u32 v244, v144, 4, 2
	v_lshl_or_b32 v112, v244, 5, v243
	v_mov_b32_e32 v113, 0
	v_lshl_add_u64 v[124:125], v[154:155], 0, v[112:113]
	global_load_dwordx4 v[112:115], v[116:117], off
	s_nop 0
	global_load_dwordx4 v[116:119], v[116:117], off offset:16
	s_nop 0
	global_load_dwordx4 v[120:123], v[124:125], off
	s_nop 0
	global_load_dwordx4 v[124:127], v[124:125], off offset:16
	v_lshl_add_u64 v[142:143], v[158:159], 0, v[128:129]
	global_load_dwordx2 v[128:129], v[142:143], off
	global_load_dwordx2 v[130:131], v[142:143], off offset:512
	global_load_dwordx2 v[132:133], v[142:143], off offset:128
	global_load_dwordx2 v[134:135], v[142:143], off offset:640
	global_load_dwordx2 v[136:137], v[142:143], off offset:256
	global_load_dwordx2 v[138:139], v[142:143], off offset:768
	global_load_dwordx2 v[140:141], v[142:143], off offset:384
	s_nop 0
	global_load_dwordx2 v[142:143], v[142:143], off offset:896
	ds_read_b128 v[184:187], v228 offset:2048
	ds_read_b128 v[188:191], v228 offset:3072
	s_waitcnt vmcnt(21) lgkmcnt(1)
	v_mfma_f32_16x16x32_bf16 v[100:103], v[100:103], v[184:187], 0
	s_sub_i32 s0, s1, 64
	v_add_u32_e32 v144, s11, v246
	v_mfma_f32_16x16x32_bf16 v[108:111], v[108:111], v[184:187], 0
	v_lshl_add_u32 v144, v144, 3, s0
	v_add_u32_e32 v181, 32, v181
	s_waitcnt vmcnt(20) lgkmcnt(0)
; __device__ __forceinline__ void attn_step(int ks, const KVB& b, int L16, int r, int i0, int iq, int lane,
;                                           const bf16x8* qs, f32x4 (&o)[4], float& mrun, float& lrun) {
;   asm volatile("" : "+v"(lane), "+v"(iq));
;   asm volatile("" : "+s"(r), "+s"(i0));
;   const int quad = lane >> 4;
;   bf16x8 qB0 = qs[0], qB1 = qs[64];
;   int cV, sV; attn_desc(ks, quad, r, i0, cV, sV);
;   int D = ks < 12 ? 4 : (ks < 18 ? 16 : 64);
;   f32x4 z = {0.f, 0.f, 0.f, 0.f};
;   f32x4 sa = __builtin_amdgcn_mfma_f32_16x16x32_bf16(b.k0, qB0, z, 0, 0, 0);
;   sa = __builtin_amdgcn_mfma_f32_16x16x32_bf16(b.k1, qB1, sa, 0, 0, 0);
;   f32x4 sb = __builtin_amdgcn_mfma_f32_16x16x32_bf16(b.k2, qB0, z, 0, 0, 0);
;   sb = __builtin_amdgcn_mfma_f32_16x16x32_bf16(b.k3, qB1, sb, 0, 0, 0);
;   int jlo = max(iq - D + (cV < r ? 1 : 0), 0) - sV;
;   int jhi = min(iq + D - (cV > r ? 1 : 0), L16 - 1) - sV;
;   const float NINF = -__builtin_inff();
;   float s8[8];
;   float mt = -1e30f;
; #pragma unroll
;   for (int j = 0; j < 8; ++j) {
;     float sv = j < 4 ? sa[j] : sb[j - 4];
;     sv = (j >= jlo && j <= jhi) ? sv : NINF;
;     s8[j] = sv;
;     mt = fmaxf(mt, sv);
;   }
;   mt = fmaxf(mt, __shfl_xor(mt, 16));
;   mt = fmaxf(mt, __shfl_xor(mt, 32));
;   float mnew = fmaxf(mrun, mt);
;   float alpha = __builtin_amdgcn_exp2f(mrun - mnew);
;   mrun = mnew;
;   float ps = 0.f;
;   float p8[8];
; #pragma unroll
;   for (int j = 0; j < 8; ++j) { p8[j] = __builtin_amdgcn_exp2f(s8[j] - mnew); ps += p8[j]; }
;   lrun = lrun * alpha + ps;
;   union { uint4 u; bf16x8 v; } pb;
;   pb.u = make_uint4(pack2(p8[0], p8[1]), pack2(p8[2], p8[3]), pack2(p8[4], p8[5]), pack2(p8[6], p8[7]));
; #pragma unroll
;   for (int dt = 0; dt < 4; ++dt) { o[dt][0] *= alpha; o[dt][1] *= alpha; o[dt][2] *= alpha; o[dt][3] *= alpha; }
;   o[0] = __builtin_amdgcn_mfma_f32_16x16x32_bf16(b.v0, pb.v, o[0], 0, 0, 0);
;   o[1] = __builtin_amdgcn_mfma_f32_16x16x32_bf16(b.v1, pb.v, o[1], 0, 0, 0);
;   o[2] = __builtin_amdgcn_mfma_f32_16x16x32_bf16(b.v2, pb.v, o[2], 0, 0, 0);
;   o[3] = __builtin_amdgcn_mfma_f32_16x16x32_bf16(b.v3, pb.v, o[3], 0, 0, 0);
; }
	v_mfma_f32_16x16x32_bf16 v[96:99], v[96:99], v[188:191], v[100:103]
	s_nop 2
	v_subrev_u32_e32 v100, 64, v225
	v_add_u32_e32 v101, 64, v225
	v_mfma_f32_16x16x32_bf16 v[104:107], v[104:107], v[188:191], v[108:111]
	v_max_i32_e32 v100, 0, v100
	v_min_i32_e32 v101, s43, v101
	v_sub_u32_e32 v100, v100, v144
	v_sub_u32_e32 v101, v101, v144
	v_cmp_lt_i32_e32 vcc, 0, v100
	v_cmp_gt_i32_e64 s[0:1], 0, v101
	s_or_b64 vcc, vcc, s[0:1]
	s_nop 0
	v_cndmask_b32_e32 v102, v104, v219, vcc
	v_cmp_lt_i32_e32 vcc, 1, v100
	v_cmp_gt_i32_e64 s[0:1], 1, v101
	s_or_b64 vcc, vcc, s[0:1]
	v_cndmask_b32_e32 v103, v105, v219, vcc
	v_cmp_lt_i32_e32 vcc, 2, v100
	v_cmp_gt_i32_e64 s[0:1], 2, v101
	s_or_b64 vcc, vcc, s[0:1]
	v_cndmask_b32_e32 v105, v106, v219, vcc
	v_cmp_lt_i32_e32 vcc, 3, v100
	v_cmp_gt_i32_e64 s[0:1], 3, v101
	s_or_b64 vcc, vcc, s[0:1]
	v_cndmask_b32_e32 v106, v107, v219, vcc
	v_cmp_lt_i32_e32 vcc, 4, v100
	v_cmp_gt_i32_e64 s[0:1], 4, v101
	s_or_b64 vcc, vcc, s[0:1]
	v_cndmask_b32_e32 v96, v96, v219, vcc
	v_cmp_lt_i32_e32 vcc, 5, v100
	v_cmp_gt_i32_e64 s[0:1], 5, v101
	s_or_b64 vcc, vcc, s[0:1]
	v_cndmask_b32_e32 v97, v97, v219, vcc
	v_cmp_lt_i32_e32 vcc, 6, v100
	v_cmp_gt_i32_e64 s[0:1], 6, v101
	s_or_b64 vcc, vcc, s[0:1]
	v_max3_f32 v104, v102, s41, v103
	v_cndmask_b32_e32 v98, v98, v219, vcc
	v_cmp_lt_i32_e32 vcc, 7, v100
	v_cmp_gt_i32_e64 s[0:1], 7, v101
	v_max3_f32 v104, v104, v105, v106
	s_or_b64 vcc, vcc, s[0:1]
	v_max3_f32 v104, v104, v96, v97
	v_cndmask_b32_e32 v99, v99, v219, vcc
	v_max3_f32 v100, v104, v98, v99
	v_mov_b32_e32 v101, v100
	s_nop 1
	v_permlane16_swap_b32_e32 v100, v101
	v_add_u32_e32 v144, s10, v194
	s_mov_b32 s0, s8
	s_mov_b32 s1, s46
	s_waitcnt lgkmcnt(0)
	v_max_f32_e32 v100, v100, v101
	v_mov_b32_e32 v101, v100
	s_nop 1
	v_permlane32_swap_b32_e32 v100, v101
	s_waitcnt lgkmcnt(0)
	v_max3_f32 v183, v237, v100, v101
	v_sub_f32_e32 v101, v102, v183
	v_exp_f32_e32 v162, v101
	v_sub_f32_e32 v101, v103, v183
	v_sub_f32_e32 v96, v96, v183
	v_exp_f32_e32 v164, v101
	v_sub_f32_e32 v101, v105, v183
	v_exp_f32_e32 v170, v96
	v_sub_f32_e32 v96, v97, v183
	v_exp_f32_e32 v166, v101
	v_sub_f32_e32 v101, v106, v183
	v_exp_f32_e32 v172, v96
	v_sub_f32_e32 v96, v98, v183
	v_exp_f32_e32 v168, v101
	v_exp_f32_e32 v174, v96
	v_sub_f32_e32 v96, v99, v183
	v_exp_f32_e32 v176, v96
	v_pk_add_f32 v[96:97], v[162:163], 0 op_sel_hi:[1,0]
	v_sub_f32_e32 v100, v237, v183
	v_pk_add_f32 v[96:97], v[164:165], v[96:97]
	v_exp_f32_e32 v178, v100
	v_pk_add_f32 v[96:97], v[166:167], v[96:97]
	v_cvt_pk_bf16_f32 v98, v171, v173
	v_pk_add_f32 v[96:97], v[168:169], v[96:97]
	v_cvt_pk_bf16_f32 v99, v175, v177
	v_pk_add_f32 v[96:97], v[170:171], v[96:97]
	v_pk_mul_f32 v[50:51], v[50:51], v[178:179] op_sel_hi:[1,0]
	v_pk_add_f32 v[96:97], v[172:173], v[96:97]
	v_pk_mul_f32 v[48:49], v[48:49], v[178:179] op_sel_hi:[1,0]
	v_pk_add_f32 v[96:97], v[174:175], v[96:97]
	v_pk_mul_f32 v[42:43], v[42:43], v[178:179] op_sel_hi:[1,0]
	v_pk_add_f32 v[100:101], v[176:177], v[96:97]
	v_mov_b32_e32 v96, v179
	v_pk_mul_f32 v[62:63], v[62:63], v[96:97] op_sel_hi:[1,0]
	v_pk_mul_f32 v[60:61], v[60:61], v[96:97] op_sel_hi:[1,0]
	v_pk_mul_f32 v[58:59], v[58:59], v[96:97] op_sel_hi:[1,0]
	v_pk_mul_f32 v[56:57], v[56:57], v[96:97] op_sel_hi:[1,0]
	v_pk_mul_f32 v[54:55], v[54:55], v[96:97] op_sel_hi:[1,0]
	v_pk_mul_f32 v[52:53], v[52:53], v[96:97] op_sel_hi:[1,0]
	v_pk_mul_f32 v[46:47], v[46:47], v[96:97] op_sel_hi:[1,0]
	v_pk_mul_f32 v[44:45], v[44:45], v[96:97] op_sel_hi:[1,0]
	v_cvt_pk_bf16_f32 v96, v163, v165
	v_cvt_pk_bf16_f32 v97, v167, v169
	v_pk_mul_f32 v[40:41], v[40:41], v[178:179] op_sel_hi:[1,0]
	v_pk_mul_f32 v[38:39], v[38:39], v[178:179] op_sel_hi:[1,0]
	v_mfma_f32_16x16x32_bf16 v[60:63], v[64:67], v[96:99], v[60:63]
	v_mul_f32_e64 v36, v36, v178
	v_mul_f32_e64 v37, v37, v178
	v_pk_mul_f32 v[30:31], v[30:31], v[178:179] op_sel_hi:[1,0]
	v_pk_mul_f32 v[28:29], v[28:29], v[178:179] op_sel_hi:[1,0]
	v_cvt_pk_bf16_f32 v64, v162, v164
	v_cvt_pk_bf16_f32 v65, v166, v168
	v_cvt_pk_bf16_f32 v66, v170, v172
	v_cvt_pk_bf16_f32 v67, v174, v176
	v_mfma_f32_16x16x32_bf16 v[56:59], v[68:71], v[96:99], v[56:59]
	v_fma_f32 v160, v160, v178, v100
	v_fma_f32 v161, v161, v179, v101
	s_waitcnt vmcnt(15)
	v_mfma_f32_16x16x32_bf16 v[48:51], v[80:83], v[64:67], v[48:51]
	v_mov_b32_e32 v237, v183
	s_waitcnt vmcnt(14)
	v_mfma_f32_16x16x32_bf16 v[40:43], v[84:87], v[64:67], v[40:43]
	s_waitcnt vmcnt(13)
	v_mfma_f32_16x16x32_bf16 v[36:39], v[88:91], v[64:67], v[36:39]
	s_waitcnt vmcnt(12)
	v_mfma_f32_16x16x32_bf16 v[28:31], v[92:95], v[64:67], v[28:31]
	v_lshrrev_b32_e32 v243, 8, v144
	v_and_b32_e32 v244, 15, v144
	v_lshlrev_b32_e32 v243, 18, v243
	v_lshl_or_b32 v243, v244, 11, v243
	v_bfe_u32 v244, v144, 6, 2
	v_lshl_or_b32 v243, v244, 9, v243
	v_bfe_u32 v244, v144, 4, 2
	v_lshl_or_b32 v64, v244, 5, v243
	v_mov_b32_e32 v65, 0
	v_add_u32_e32 v144, s10, v195
	v_lshl_add_u64 v[64:65], v[154:155], 0, v[64:65]
	v_lshrrev_b32_e32 v243, 8, v144
	v_and_b32_e32 v244, 15, v144
	v_lshlrev_b32_e32 v243, 18, v243
	v_lshl_or_b32 v243, v244, 11, v243
	v_bfe_u32 v244, v144, 6, 2
	v_lshl_or_b32 v243, v244, 9, v243
	v_bfe_u32 v244, v144, 4, 2
	v_lshl_or_b32 v66, v244, 5, v243
	v_mov_b32_e32 v67, 0
	v_mfma_f32_16x16x32_bf16 v[52:55], v[72:75], v[96:99], v[52:55]
	v_lshl_add_u64 v[66:67], v[154:155], 0, v[66:67]
	v_mfma_f32_16x16x32_bf16 v[44:47], v[76:79], v[96:99], v[44:47]
	global_load_dwordx4 v[96:99], v[64:65], off
	global_load_dwordx4 v[100:103], v[64:65], off offset:16
	global_load_dwordx4 v[104:107], v[66:67], off
	global_load_dwordx4 v[108:111], v[66:67], off offset:16
	v_lshl_add_u64 v[64:65], s[20:21], 0, v[192:193]
	v_lshlrev_b64 v[64:65], 9, v[64:65]
	v_lshl_add_u64 v[64:65], v[158:159], 0, v[64:65]
	global_load_dwordx2 v[80:81], v[64:65], off
	global_load_dwordx2 v[82:83], v[64:65], off offset:512
	global_load_dwordx2 v[84:85], v[64:65], off offset:128
	global_load_dwordx2 v[86:87], v[64:65], off offset:640
	global_load_dwordx2 v[88:89], v[64:65], off offset:256
	global_load_dwordx2 v[90:91], v[64:65], off offset:768
	global_load_dwordx2 v[92:93], v[64:65], off offset:384
	global_load_dwordx2 v[94:95], v[64:65], off offset:896
	ds_read_b128 v[64:67], v228 offset:4096
	ds_read_b128 v[68:71], v228 offset:5120
	s_sub_i32 s0, s1, 64
	v_add_u32_e32 v72, s11, v246
	v_lshl_add_u32 v77, v72, 3, s0
	s_waitcnt vmcnt(23) lgkmcnt(1)
; __device__ __forceinline__ void attn_step(int ks, const KVB& b, int L16, int r, int i0, int iq, int lane,
;                                           const bf16x8* qs, f32x4 (&o)[4], float& mrun, float& lrun) {
;   asm volatile("" : "+v"(lane), "+v"(iq));
;   asm volatile("" : "+s"(r), "+s"(i0));
;   const int quad = lane >> 4;
;   bf16x8 qB0 = qs[0], qB1 = qs[64];
;   int cV, sV; attn_desc(ks, quad, r, i0, cV, sV);
;   int D = ks < 12 ? 4 : (ks < 18 ? 16 : 64);
;   f32x4 z = {0.f, 0.f, 0.f, 0.f};
;   f32x4 sa = __builtin_amdgcn_mfma_f32_16x16x32_bf16(b.k0, qB0, z, 0, 0, 0);
;   sa = __builtin_amdgcn_mfma_f32_16x16x32_bf16(b.k1, qB1, sa, 0, 0, 0);
;   f32x4 sb = __builtin_amdgcn_mfma_f32_16x16x32_bf16(b.k2, qB0, z, 0, 0, 0);
;   sb = __builtin_amdgcn_mfma_f32_16x16x32_bf16(b.k3, qB1, sb, 0, 0, 0);
;   int jlo = max(iq - D + (cV < r ? 1 : 0), 0) - sV;
;   int jhi = min(iq + D - (cV > r ? 1 : 0), L16 - 1) - sV;
;   const float NINF = -__builtin_inff();
;   float s8[8];
;   float mt = -1e30f;
; #pragma unroll
;   for (int j = 0; j < 8; ++j) {
;     float sv = j < 4 ? sa[j] : sb[j - 4];
;     sv = (j >= jlo && j <= jhi) ? sv : NINF;
;     s8[j] = sv;
;     mt = fmaxf(mt, sv);
;   }
;   mt = fmaxf(mt, __shfl_xor(mt, 16));
;   mt = fmaxf(mt, __shfl_xor(mt, 32));
;   float mnew = fmaxf(mrun, mt);
;   float alpha = __builtin_amdgcn_exp2f(mrun - mnew);
;   mrun = mnew;
;   float ps = 0.f;
;   float p8[8];
; #pragma unroll
;   for (int j = 0; j < 8; ++j) { p8[j] = __builtin_amdgcn_exp2f(s8[j] - mnew); ps += p8[j]; }
;   lrun = lrun * alpha + ps;
;   union { uint4 u; bf16x8 v; } pb;
;   pb.u = make_uint4(pack2(p8[0], p8[1]), pack2(p8[2], p8[3]), pack2(p8[4], p8[5]), pack2(p8[6], p8[7]));
; #pragma unroll
;   for (int dt = 0; dt < 4; ++dt) { o[dt][0] *= alpha; o[dt][1] *= alpha; o[dt][2] *= alpha; o[dt][3] *= alpha; }
;   o[0] = __builtin_amdgcn_mfma_f32_16x16x32_bf16(b.v0, pb.v, o[0], 0, 0, 0);
;   o[1] = __builtin_amdgcn_mfma_f32_16x16x32_bf16(b.v1, pb.v, o[1], 0, 0, 0);
;   o[2] = __builtin_amdgcn_mfma_f32_16x16x32_bf16(b.v2, pb.v, o[2], 0, 0, 0);
;   o[3] = __builtin_amdgcn_mfma_f32_16x16x32_bf16(b.v3, pb.v, o[3], 0, 0, 0);
; }
; template <int NT>
; __device__ void attn_unitN(const P& p, int u) {
;     ...
;   for (int kk = 0; kk < 5; ++kk) {
;     int e0 = 18 + NT * kk, ks = 18 + kk;
; #pragma unroll
;     for (int t = 0; t < NT; t += 2) {
	v_mfma_f32_16x16x32_bf16 v[72:75], v[112:115], v[64:67], 0
	s_waitcnt vmcnt(21)
	v_mfma_f32_16x16x32_bf16 v[64:67], v[120:123], v[64:67], 0
	s_waitcnt lgkmcnt(0)
	v_mfma_f32_16x16x32_bf16 v[72:75], v[116:119], v[68:71], v[72:75]
	s_waitcnt vmcnt(20)
	v_mfma_f32_16x16x32_bf16 v[64:67], v[124:127], v[68:71], v[64:67]
	v_subrev_u32_e32 v68, 64, v225
	v_add_u32_e32 v69, 64, v225
	v_max_i32_e32 v68, 0, v68
	v_min_i32_e32 v69, s43, v69
	v_sub_u32_e32 v68, v68, v77
	v_sub_u32_e32 v69, v69, v77
	v_cmp_lt_i32_e32 vcc, 0, v68
	v_cmp_gt_i32_e64 s[0:1], 0, v69
	s_or_b64 vcc, vcc, s[0:1]
	v_cndmask_b32_e32 v70, v72, v219, vcc
	v_cmp_lt_i32_e32 vcc, 1, v68
	v_cmp_gt_i32_e64 s[0:1], 1, v69
	s_or_b64 vcc, vcc, s[0:1]
	v_cndmask_b32_e32 v71, v73, v219, vcc
	v_cmp_lt_i32_e32 vcc, 2, v68
	v_cmp_gt_i32_e64 s[0:1], 2, v69
	s_or_b64 vcc, vcc, s[0:1]
	v_cndmask_b32_e32 v73, v74, v219, vcc
	v_cmp_lt_i32_e32 vcc, 3, v68
	v_cmp_gt_i32_e64 s[0:1], 3, v69
	s_or_b64 vcc, vcc, s[0:1]
	v_cndmask_b32_e32 v74, v75, v219, vcc
	v_cmp_lt_i32_e32 vcc, 4, v68
	v_cmp_gt_i32_e64 s[0:1], 4, v69
	s_or_b64 vcc, vcc, s[0:1]
	v_cndmask_b32_e32 v64, v64, v219, vcc
	v_cmp_lt_i32_e32 vcc, 5, v68
	v_cmp_gt_i32_e64 s[0:1], 5, v69
	s_or_b64 vcc, vcc, s[0:1]
	v_cndmask_b32_e32 v65, v65, v219, vcc
	v_cmp_lt_i32_e32 vcc, 6, v68
	v_cmp_gt_i32_e64 s[0:1], 6, v69
	s_or_b64 vcc, vcc, s[0:1]
	v_max3_f32 v72, v70, s41, v71
	v_cndmask_b32_e32 v66, v66, v219, vcc
	v_cmp_lt_i32_e32 vcc, 7, v68
	v_cmp_gt_i32_e64 s[0:1], 7, v69
	v_max3_f32 v72, v72, v73, v74
	s_or_b64 vcc, vcc, s[0:1]
	v_max3_f32 v72, v72, v64, v65
	v_cndmask_b32_e32 v67, v67, v219, vcc
	v_max3_f32 v68, v72, v66, v67
	v_mov_b32_e32 v69, v68
	s_nop 1
	v_permlane16_swap_b32_e32 v68, v69
	s_min_i32 s0, s22, 35
	s_add_i32 s0, s0, -16
	s_ashr_i32 s1, s0, 31
	s_lshr_b32 s1, s1, 30
	s_waitcnt lgkmcnt(0)
	v_max_f32_e32 v68, v68, v69
	v_mov_b32_e32 v69, v68
	s_nop 1
	v_permlane32_swap_b32_e32 v68, v69
	s_add_i32 s1, s0, s1
	s_ashr_i32 s23, s1, 2
	s_and_b32 s1, s1, 0x3ffffffc
	s_sub_i32 s0, s0, s1
	s_waitcnt lgkmcnt(0)
	v_max3_f32 v144, v236, v68, v69
	s_lshl_b32 s0, s0, 2
	v_sub_f32_e32 v69, v70, v144
	v_sub_f32_e32 v64, v64, v144
	s_add_i32 s24, s23, 18
	s_add_i32 s0, s0, s42
	v_exp_f32_e32 v163, v69
	v_sub_f32_e32 v69, v71, v144
	v_exp_f32_e32 v171, v64
	v_sub_f32_e32 v64, v65, v144
	s_cmp_gt_u32 s23, 0xffffffed
	v_exp_f32_e32 v165, v69
	v_sub_f32_e32 v69, v73, v144
	v_exp_f32_e32 v173, v64
	v_sub_f32_e32 v64, v66, v144
	s_cselect_b64 vcc, -1, 0
	s_lshl_b32 s1, s24, 3
	v_exp_f32_e32 v167, v69
	v_sub_f32_e32 v69, v74, v144
	v_exp_f32_e32 v175, v64
	v_sub_f32_e32 v64, v67, v144
	s_add_i32 s1, s1, s47
	s_lshl_b32 s23, s24, 5
	v_exp_f32_e32 v169, v69
	v_exp_f32_e32 v177, v64
	v_add_u32_e32 v64, s23, v231
	v_mov_b32_e32 v69, s1
	v_cndmask_b32_e32 v64, v64, v69, vcc
	v_sub_f32_e32 v68, v236, v144
	v_add_u32_e32 v64, v64, v227
	v_exp_f32_e32 v179, v68
	v_mov_b32_e32 v68, s0
	v_max_i32_e32 v65, 0, v64
	v_max_i32_e32 v64, -4, v64
	v_cndmask_b32_e32 v66, v68, v229, vcc
	v_min_i32_e32 v65, s43, v65
	v_add_u32_e32 v64, 4, v64
	v_min_u32_e32 v67, s43, v64
	v_lshl_add_u32 v64, v65, 4, v66
	v_ashrrev_i32_e32 v65, 31, v64
	v_lshl_add_u32 v66, v67, 4, v66
	v_lshrrev_b32_e32 v243, 8, v64
	v_and_b32_e32 v244, 15, v64
	v_lshlrev_b32_e32 v243, 18, v243
	v_lshl_or_b32 v243, v244, 11, v243
	v_bfe_u32 v244, v64, 6, 2
	v_lshl_or_b32 v243, v244, 9, v243
	v_bfe_u32 v244, v64, 4, 2
	v_lshl_or_b32 v64, v244, 5, v243
	v_mov_b32_e32 v65, 0
	v_ashrrev_i32_e32 v67, 31, v66
	v_lshl_add_u64 v[64:65], v[154:155], 0, v[64:65]
	v_lshrrev_b32_e32 v243, 8, v66
	v_and_b32_e32 v244, 15, v66
	v_lshlrev_b32_e32 v243, 18, v243
	v_lshl_or_b32 v243, v244, 11, v243
	v_bfe_u32 v244, v66, 6, 2
	v_lshl_or_b32 v243, v244, 9, v243
	v_bfe_u32 v244, v66, 4, 2
	v_lshl_or_b32 v66, v244, 5, v243
	v_mov_b32_e32 v67, 0
	v_lshl_add_u64 v[66:67], v[154:155], 0, v[66:67]
	global_load_dwordx4 v[124:127], v[64:65], off
	global_load_dwordx4 v[120:123], v[64:65], off offset:16
	global_load_dwordx4 v[116:119], v[66:67], off
	global_load_dwordx4 v[112:115], v[66:67], off offset:16
	v_add_u32_e32 v65, s23, v232
	v_cndmask_b32_e32 v64, v68, v230, vcc
	v_cndmask_b32_e32 v66, v65, v69, vcc
	v_ashrrev_i32_e32 v65, 31, v64
	v_ashrrev_i32_e32 v66, 2, v66
	v_lshlrev_b64 v[64:65], s44, v[64:65]
	v_ashrrev_i32_e32 v67, 31, v66
	v_lshl_add_u64 v[64:65], v[64:65], 0, v[66:67]
	v_lshlrev_b64 v[64:65], 9, v[64:65]
	v_lshl_add_u64 v[78:79], v[158:159], 0, v[64:65]
	s_mov_b32 s0, s10
	s_mov_b32 s1, s46
	global_load_dwordx2 v[64:65], v[78:79], off
	global_load_dwordx2 v[66:67], v[78:79], off offset:512
	global_load_dwordx2 v[68:69], v[78:79], off offset:128
	global_load_dwordx2 v[70:71], v[78:79], off offset:640
	global_load_dwordx2 v[72:73], v[78:79], off offset:256
	global_load_dwordx2 v[74:75], v[78:79], off offset:768
	global_load_dwordx2 v[76:77], v[78:79], off offset:384
	s_nop 0
	global_load_dwordx2 v[78:79], v[78:79], off offset:896
	ds_read_b128 v[184:187], v228 offset:6144
	ds_read_b128 v[188:191], v228 offset:7168
	s_waitcnt vmcnt(23) lgkmcnt(1)
	v_mfma_f32_16x16x32_bf16 v[96:99], v[96:99], v[184:187], 0
	s_sub_i32 s0, s1, 64
	v_add_u32_e32 v162, s11, v246
	s_waitcnt vmcnt(22) lgkmcnt(0)
	v_mfma_f32_16x16x32_bf16 v[96:99], v[100:103], v[188:191], v[96:99]
	v_lshl_add_u32 v162, v162, 3, s0
	v_mov_b32_e32 v236, v144
	s_waitcnt vmcnt(21)
; __device__ __forceinline__ void attn_step(int ks, const KVB& b, int L16, int r, int i0, int iq, int lane,
;                                           const bf16x8* qs, f32x4 (&o)[4], float& mrun, float& lrun) {
;   asm volatile("" : "+v"(lane), "+v"(iq));
;   asm volatile("" : "+s"(r), "+s"(i0));
;   const int quad = lane >> 4;
;   bf16x8 qB0 = qs[0], qB1 = qs[64];
;   int cV, sV; attn_desc(ks, quad, r, i0, cV, sV);
;   int D = ks < 12 ? 4 : (ks < 18 ? 16 : 64);
;   f32x4 z = {0.f, 0.f, 0.f, 0.f};
;   f32x4 sa = __builtin_amdgcn_mfma_f32_16x16x32_bf16(b.k0, qB0, z, 0, 0, 0);
;   sa = __builtin_amdgcn_mfma_f32_16x16x32_bf16(b.k1, qB1, sa, 0, 0, 0);
;   f32x4 sb = __builtin_amdgcn_mfma_f32_16x16x32_bf16(b.k2, qB0, z, 0, 0, 0);
;   sb = __builtin_amdgcn_mfma_f32_16x16x32_bf16(b.k3, qB1, sb, 0, 0, 0);
;   int jlo = max(iq - D + (cV < r ? 1 : 0), 0) - sV;
;   int jhi = min(iq + D - (cV > r ? 1 : 0), L16 - 1) - sV;
;   const float NINF = -__builtin_inff();
;   float s8[8];
;   float mt = -1e30f;
; #pragma unroll
;   for (int j = 0; j < 8; ++j) {
;     float sv = j < 4 ? sa[j] : sb[j - 4];
;     sv = (j >= jlo && j <= jhi) ? sv : NINF;
;     s8[j] = sv;
;     mt = fmaxf(mt, sv);
;   }
;   mt = fmaxf(mt, __shfl_xor(mt, 16));
;   mt = fmaxf(mt, __shfl_xor(mt, 32));
;   float mnew = fmaxf(mrun, mt);
;   float alpha = __builtin_amdgcn_exp2f(mrun - mnew);
;   mrun = mnew;
;   float ps = 0.f;
;   float p8[8];
; #pragma unroll
;   for (int j = 0; j < 8; ++j) { p8[j] = __builtin_amdgcn_exp2f(s8[j] - mnew); ps += p8[j]; }
;   lrun = lrun * alpha + ps;
;   union { uint4 u; bf16x8 v; } pb;
;   pb.u = make_uint4(pack2(p8[0], p8[1]), pack2(p8[2], p8[3]), pack2(p8[4], p8[5]), pack2(p8[6], p8[7]));
; #pragma unroll
;   for (int dt = 0; dt < 4; ++dt) { o[dt][0] *= alpha; o[dt][1] *= alpha; o[dt][2] *= alpha; o[dt][3] *= alpha; }
;   o[0] = __builtin_amdgcn_mfma_f32_16x16x32_bf16(b.v0, pb.v, o[0], 0, 0, 0);
;   o[1] = __builtin_amdgcn_mfma_f32_16x16x32_bf16(b.v1, pb.v, o[1], 0, 0, 0);
;   o[2] = __builtin_amdgcn_mfma_f32_16x16x32_bf16(b.v2, pb.v, o[2], 0, 0, 0);
;   o[3] = __builtin_amdgcn_mfma_f32_16x16x32_bf16(b.v3, pb.v, o[3], 0, 0, 0);
; }
	v_mfma_f32_16x16x32_bf16 v[100:103], v[104:107], v[184:187], 0
	v_subrev_u32_e32 v104, 64, v225
	v_add_u32_e32 v105, 64, v225
	v_max_i32_e32 v104, 0, v104
	v_min_i32_e32 v105, s43, v105
	v_sub_u32_e32 v104, v104, v162
	v_sub_u32_e32 v105, v105, v162
	v_cmp_lt_i32_e32 vcc, 0, v104
	v_cmp_gt_i32_e64 s[0:1], 0, v105
	s_or_b64 vcc, vcc, s[0:1]
	v_cndmask_b32_e32 v96, v96, v219, vcc
	v_cmp_lt_i32_e32 vcc, 1, v104
	v_cmp_gt_i32_e64 s[0:1], 1, v105
	s_or_b64 vcc, vcc, s[0:1]
	v_cndmask_b32_e32 v97, v97, v219, vcc
	v_cmp_lt_i32_e32 vcc, 2, v104
	v_cmp_gt_i32_e64 s[0:1], 2, v105
	s_or_b64 vcc, vcc, s[0:1]
	s_waitcnt vmcnt(20)
	v_mfma_f32_16x16x32_bf16 v[100:103], v[108:111], v[188:191], v[100:103]
	v_cndmask_b32_e32 v98, v98, v219, vcc
	v_cmp_lt_i32_e32 vcc, 3, v104
	v_cmp_gt_i32_e64 s[0:1], 3, v105
	s_or_b64 vcc, vcc, s[0:1]
	v_cndmask_b32_e32 v99, v99, v219, vcc
	v_cmp_lt_i32_e32 vcc, 4, v104
	v_cmp_gt_i32_e64 s[0:1], 4, v105
	s_or_b64 vcc, vcc, s[0:1]
	v_cndmask_b32_e32 v100, v100, v219, vcc
	v_cmp_lt_i32_e32 vcc, 5, v104
	v_cmp_gt_i32_e64 s[0:1], 5, v105
	s_or_b64 vcc, vcc, s[0:1]
	v_cndmask_b32_e32 v101, v101, v219, vcc
	v_cmp_lt_i32_e32 vcc, 6, v104
	v_cmp_gt_i32_e64 s[0:1], 6, v105
	s_or_b64 vcc, vcc, s[0:1]
	v_max3_f32 v106, v96, s41, v97
	v_cndmask_b32_e32 v102, v102, v219, vcc
	v_cmp_lt_i32_e32 vcc, 7, v104
	v_cmp_gt_i32_e64 s[0:1], 7, v105
	v_max3_f32 v106, v106, v98, v99
	s_or_b64 vcc, vcc, s[0:1]
	v_max3_f32 v106, v106, v100, v101
	v_cndmask_b32_e32 v103, v103, v219, vcc
	v_max3_f32 v104, v106, v102, v103
	v_mov_b32_e32 v105, v104
	s_nop 1
	v_permlane16_swap_b32_e32 v104, v105
	s_min_i32 s0, s22, 34
	s_add_i32 s0, s0, -15
	s_ashr_i32 s1, s0, 31
	s_lshr_b32 s1, s1, 30
	s_waitcnt lgkmcnt(0)
	v_max_f32_e32 v104, v104, v105
	v_mov_b32_e32 v105, v104
	s_nop 1
	v_permlane32_swap_b32_e32 v104, v105
	s_add_i32 s1, s0, s1
	s_ashr_i32 s22, s1, 2
	s_and_b32 s1, s1, 0x3ffffffc
	s_sub_i32 s0, s0, s1
	s_waitcnt lgkmcnt(0)
	v_max3_f32 v184, v235, v104, v105
	v_sub_f32_e32 v96, v96, v184
	v_exp_f32_e32 v162, v96
	v_sub_f32_e32 v96, v97, v184
	v_exp_f32_e32 v164, v96
	v_sub_f32_e32 v96, v98, v184
	v_exp_f32_e32 v166, v96
	v_sub_f32_e32 v96, v99, v184
	v_exp_f32_e32 v168, v96
	v_sub_f32_e32 v96, v100, v184
	v_exp_f32_e32 v170, v96
	v_sub_f32_e32 v96, v101, v184
	v_exp_f32_e32 v172, v96
	v_sub_f32_e32 v96, v102, v184
	v_exp_f32_e32 v174, v96
	v_sub_f32_e32 v96, v103, v184
	v_exp_f32_e32 v176, v96
	v_pk_add_f32 v[96:97], v[162:163], 0 op_sel_hi:[1,0]
	v_sub_f32_e32 v104, v235, v184
	v_pk_add_f32 v[96:97], v[164:165], v[96:97]
	v_exp_f32_e32 v178, v104
	v_pk_add_f32 v[96:97], v[166:167], v[96:97]
	s_lshl_b32 s0, s0, 2
	v_pk_add_f32 v[96:97], v[168:169], v[96:97]
	s_add_i32 s23, s22, 18
	v_pk_add_f32 v[96:97], v[170:171], v[96:97]
	s_add_i32 s0, s0, s42
	v_pk_add_f32 v[96:97], v[172:173], v[96:97]
	s_cmp_gt_u32 s22, 0xffffffed
	v_pk_add_f32 v[96:97], v[174:175], v[96:97]
	v_cvt_pk_bf16_f32 v98, v171, v173
	v_pk_add_f32 v[100:101], v[176:177], v[96:97]
	v_mov_b32_e32 v96, v179
	v_pk_mul_f32 v[34:35], v[34:35], v[96:97] op_sel_hi:[1,0]
	v_pk_mul_f32 v[32:33], v[32:33], v[96:97] op_sel_hi:[1,0]
	v_pk_mul_f32 v[26:27], v[26:27], v[96:97] op_sel_hi:[1,0]
	v_pk_mul_f32 v[24:25], v[24:25], v[96:97] op_sel_hi:[1,0]
	v_pk_mul_f32 v[22:23], v[22:23], v[96:97] op_sel_hi:[1,0]
	v_pk_mul_f32 v[20:21], v[20:21], v[96:97] op_sel_hi:[1,0]
	v_pk_mul_f32 v[14:15], v[14:15], v[96:97] op_sel_hi:[1,0]
	v_pk_mul_f32 v[12:13], v[12:13], v[96:97] op_sel_hi:[1,0]
	v_cvt_pk_bf16_f32 v96, v163, v165
	v_cvt_pk_bf16_f32 v97, v167, v169
	v_cvt_pk_bf16_f32 v99, v175, v177
	s_cselect_b64 vcc, -1, 0
	s_lshl_b32 s1, s23, 3
	v_mfma_f32_16x16x32_bf16 v[32:35], v[128:131], v[96:99], v[32:35]
	v_mul_f32_e64 v18, v18, v178
	v_mul_f32_e64 v19, v19, v178
	v_pk_mul_f32 v[16:17], v[16:17], v[178:179] op_sel_hi:[1,0]
	v_pk_mul_f32 v[10:11], v[10:11], v[178:179] op_sel_hi:[1,0]
	v_mfma_f32_16x16x32_bf16 v[24:27], v[132:135], v[96:99], v[24:27]
	v_mul_f32_e64 v8, v8, v178
	v_mul_f32_e64 v9, v9, v178
	s_add_i32 s1, s1, s47
	s_lshl_b32 s22, s23, 5
	v_mfma_f32_16x16x32_bf16 v[20:23], v[136:139], v[96:99], v[20:23]
	v_mul_f32_e64 v6, v6, v178
	v_mul_f32_e64 v7, v7, v178
	v_pk_mul_f32 v[4:5], v[4:5], v[178:179] op_sel_hi:[1,0]
	v_pk_mul_f32 v[2:3], v[2:3], v[178:179] op_sel_hi:[1,0]
	v_mfma_f32_16x16x32_bf16 v[12:15], v[140:143], v[96:99], v[12:15]
	v_cvt_pk_bf16_f32 v96, v162, v164
	v_cvt_pk_bf16_f32 v97, v166, v168
	v_cvt_pk_bf16_f32 v98, v170, v172
	v_cvt_pk_bf16_f32 v99, v174, v176
	v_pk_mul_f32 v[0:1], v[0:1], v[178:179] op_sel_hi:[1,0]
	v_pk_fma_f32 v[156:157], v[156:157], v[178:179], v[100:101]
	s_waitcnt vmcnt(18)
; __device__ __forceinline__ KVB attn_load(int ks, const u16* __restrict__ kbase, const u16* __restrict__ vbase, int L16,
;                                          int r, int i0, int lane) {
;   KVB b;
;   const int quad = lane >> 4, l15 = lane & 15, gk = l15 >> 2, ek = l15 & 3;
;   int cK, sK; attn_desc(ks, gk, r, i0, cK, sK);
;   int ia = sK + ek, ib = ia + 4;
;   ia = min(max(ia, 0), L16 - 1); ib = min(max(ib, 0), L16 - 1);
;   const u16* ka = kbase + (size_t)(cK + 16 * ia) * 512;
;   const u16* kb = kbase + (size_t)(cK + 16 * ib) * 512;
;   b.k0 = *(const bf16x8*)ka; b.k1 = *(const bf16x8*)(ka + 8);
;   b.k2 = *(const bf16x8*)kb; b.k3 = *(const bf16x8*)(kb + 8);
;   int cV, sV; attn_desc(ks, quad, r, i0, cV, sV);
;   const u16* vp = vbase + ((ptrdiff_t)cV * (L16 >> 2) + (sV >> 2)) * 256 + l15 * 4;
;   {
;     union { struct { uint2 a, b; } p; bf16x8 v; } c0, c1, c2, c3;
;     c0.p.a = *(const uint2*)(vp);        c0.p.b = *(const uint2*)(vp + 256);
;     c1.p.a = *(const uint2*)(vp + 64);   c1.p.b = *(const uint2*)(vp + 64 + 256);
;     c2.p.a = *(const uint2*)(vp + 128);  c2.p.b = *(const uint2*)(vp + 128 + 256);
;     c3.p.a = *(const uint2*)(vp + 192);  c3.p.b = *(const uint2*)(vp + 192 + 256);
;     b.v0 = c0.v; b.v1 = c1.v; b.v2 = c2.v; b.v3 = c3.v;
;   }
;   return b;
; }
; __device__ __forceinline__ void attn_step(int ks, const KVB& b, int L16, int r, int i0, int iq, int lane,
;                                           const bf16x8* qs, f32x4 (&o)[4], float& mrun, float& lrun) {
;     ...
; #pragma unroll
;   for (int dt = 0; dt < 4; ++dt) { o[dt][0] *= alpha; o[dt][1] *= alpha; o[dt][2] *= alpha; o[dt][3] *= alpha; }
;   o[0] = __builtin_amdgcn_mfma_f32_16x16x32_bf16(b.v0, pb.v, o[0], 0, 0, 0);
;   o[1] = __builtin_amdgcn_mfma_f32_16x16x32_bf16(b.v1, pb.v, o[1], 0, 0, 0);
;   o[2] = __builtin_amdgcn_mfma_f32_16x16x32_bf16(b.v2, pb.v, o[2], 0, 0, 0);
;   o[3] = __builtin_amdgcn_mfma_f32_16x16x32_bf16(b.v3, pb.v, o[3], 0, 0, 0);
	v_mfma_f32_16x16x32_bf16 v[16:19], v[80:83], v[96:99], v[16:19]
	v_add_u32_e32 v80, s22, v231
	s_add_i32 s11, s11, 4
	s_cmp_lg_u32 s11, 20
	s_waitcnt vmcnt(16)
	v_mfma_f32_16x16x32_bf16 v[8:11], v[84:87], v[96:99], v[8:11]
	v_mov_b32_e32 v85, s1
	v_cndmask_b32_e32 v80, v80, v85, vcc
	v_add_u32_e32 v80, v80, v227
	v_mov_b32_e32 v84, s0
	v_max_i32_e32 v81, 0, v80
	v_max_i32_e32 v80, -4, v80
	v_cndmask_b32_e32 v82, v84, v229, vcc
	v_min_i32_e32 v81, s43, v81
	v_add_u32_e32 v80, 4, v80
	v_min_u32_e32 v83, s43, v80
	v_lshl_add_u32 v80, v81, 4, v82
	v_ashrrev_i32_e32 v81, 31, v80
	v_lshl_add_u32 v82, v83, 4, v82
	v_lshrrev_b32_e32 v243, 8, v80
	v_and_b32_e32 v244, 15, v80
	v_lshlrev_b32_e32 v243, 18, v243
	v_lshl_or_b32 v243, v244, 11, v243
	v_bfe_u32 v244, v80, 6, 2
	v_lshl_or_b32 v243, v244, 9, v243
	v_bfe_u32 v244, v80, 4, 2
	v_lshl_or_b32 v80, v244, 5, v243
	v_mov_b32_e32 v81, 0
	v_ashrrev_i32_e32 v83, 31, v82
	v_lshl_add_u64 v[80:81], v[154:155], 0, v[80:81]
	v_lshrrev_b32_e32 v243, 8, v82
	v_and_b32_e32 v244, 15, v82
	v_lshlrev_b32_e32 v243, 18, v243
	v_lshl_or_b32 v243, v244, 11, v243
	v_bfe_u32 v244, v82, 6, 2
	v_lshl_or_b32 v243, v244, 9, v243
	v_bfe_u32 v244, v82, 4, 2
	v_lshl_or_b32 v82, v244, 5, v243
	v_mov_b32_e32 v83, 0
	s_waitcnt vmcnt(14)
	v_mfma_f32_16x16x32_bf16 v[4:7], v[88:91], v[96:99], v[4:7]
	v_lshl_add_u64 v[82:83], v[154:155], 0, v[82:83]
	v_mov_b32_e32 v235, v184
	v_mov_b32_e32 v143, v182
	s_waitcnt vmcnt(12)
	v_mfma_f32_16x16x32_bf16 v[0:3], v[92:95], v[96:99], v[0:3]
	global_load_dwordx4 v[108:111], v[80:81], off
	global_load_dwordx4 v[104:107], v[80:81], off offset:16
	global_load_dwordx4 v[100:103], v[82:83], off
	global_load_dwordx4 v[96:99], v[82:83], off offset:16
	v_add_u32_e32 v81, s22, v232
	v_cndmask_b32_e32 v80, v84, v230, vcc
	v_cndmask_b32_e32 v82, v81, v85, vcc
	v_ashrrev_i32_e32 v81, 31, v80
	v_ashrrev_i32_e32 v82, 2, v82
	v_lshlrev_b64 v[80:81], s44, v[80:81]
	v_ashrrev_i32_e32 v83, 31, v82
	v_lshl_add_u64 v[80:81], v[80:81], 0, v[82:83]
	v_lshlrev_b64 v[80:81], 9, v[80:81]
	v_lshl_add_u64 v[94:95], v[158:159], 0, v[80:81]
	global_load_dwordx2 v[80:81], v[94:95], off
	global_load_dwordx2 v[82:83], v[94:95], off offset:512
	global_load_dwordx2 v[84:85], v[94:95], off offset:128
	global_load_dwordx2 v[86:87], v[94:95], off offset:640
	global_load_dwordx2 v[88:89], v[94:95], off offset:256
	global_load_dwordx2 v[90:91], v[94:95], off offset:768
	global_load_dwordx2 v[92:93], v[94:95], off offset:384
	s_nop 0
	global_load_dwordx2 v[94:95], v[94:95], off offset:896
	s_cbranch_scc1 .LBB0_267
	s_waitcnt vmcnt(19)
	ds_bpermute_b32 v64, v233, v161
	s_lshl_b32 s0, s45, 1
	s_waitcnt vmcnt(18)
	v_lshrrev_b32_e32 v66, 1, v224
	s_add_u32 s0, s34, s0
	v_and_b32_e32 v144, 24, v66
	s_waitcnt lgkmcnt(0)
	v_add_f32_e32 v67, v161, v64
	s_waitcnt vmcnt(17)
	ds_bpermute_b32 v68, v234, v67
	s_addc_u32 s1, s35, 0
	v_lshlrev_b64 v[64:65], 11, v[152:153]


; template <int NT>
; __device__ void attn_unitN(const P& p, int u) {
;     ...
;   u16* omix = (u16*)(p.ws + OFF_OMIX);
; #pragma unroll
;   for (int t = 0; t < NT; ++t) {
;     float l = lrun[t];
;     l += __shfl_xor(l, 16);
;     l += __shfl_xor(l, 32);
;     float inv = 1.f / l;
;     u16* op = omix + (size_t)(seq0 + rb + RS * t + 16 * iq) * 1024 + h * 64 + quad * 4;
; #pragma unroll
;     for (int dt = 0; dt < 4; ++dt) {
;       uint2 w; w.x = pack2(o[t][dt][0] * inv, o[t][dt][1] * inv); w.y = pack2(o[t][dt][2] * inv, o[t][dt][3] * inv);
;       *(uint2*)(op + dt * 16) = w;
;     }
;   }
; __device__ void phase_attn(const P& p) {
;   int wid = __builtin_amdgcn_readfirstlane(opaque_tid(p) >> 6);
;   for (int u = blockIdx.x * 8 + wid; u < 32768 / ATT_NT; u += gridDim.x * 8) attn_unitN<ATT_NT>(p, u);
; }
	s_waitcnt lgkmcnt(0)
	v_add_f32_e32 v68, v67, v68
	v_div_scale_f32 v69, s[4:5], v68, v68, 1.0
	s_waitcnt vmcnt(16)
	v_rcp_f32_e32 v70, v69
	v_div_scale_f32 v71, vcc, 1.0, v68, 1.0
	v_lshl_add_u64 v[66:67], s[0:1], 0, v[144:145]
	s_waitcnt vmcnt(15)
	v_fma_f32 v72, -v69, v70, 1.0
	v_fmac_f32_e32 v70, v72, v70
	v_mul_f32_e32 v72, v71, v70
	v_fma_f32 v73, -v69, v72, v71
	v_fmac_f32_e32 v72, v73, v70
	v_fma_f32 v69, -v69, v72, v71
	v_div_fmas_f32 v69, v69, v70, v72
	v_div_fixup_f32 v68, v69, v68, 1.0
	v_pk_mul_f32 v[56:57], v[56:57], v[68:69] op_sel_hi:[1,0]
	v_pk_mul_f32 v[58:59], v[58:59], v[68:69] op_sel_hi:[1,0]
	v_cvt_pk_bf16_f32 v56, v56, v57
	v_cvt_pk_bf16_f32 v57, v58, v59
	ds_bpermute_b32 v58, v233, v160
	v_lshl_add_u64 v[64:65], v[66:67], 0, v[64:65]
	global_store_dwordx2 v[64:65], v[56:57], off offset:32
	v_pk_mul_f32 v[52:53], v[52:53], v[68:69] op_sel_hi:[1,0]
	v_pk_mul_f32 v[54:55], v[54:55], v[68:69] op_sel_hi:[1,0]
	s_waitcnt lgkmcnt(0)
	v_add_f32_e32 v56, v160, v58
	ds_bpermute_b32 v57, v234, v56
	v_cvt_pk_bf16_f32 v52, v52, v53
	v_cvt_pk_bf16_f32 v53, v54, v55
	global_store_dwordx2 v[64:65], v[52:53], off offset:64
	v_pk_mul_f32 v[44:45], v[44:45], v[68:69] op_sel_hi:[1,0]
	s_waitcnt lgkmcnt(0)
	v_add_f32_e32 v52, v56, v57
	v_div_scale_f32 v53, s[0:1], v52, v52, 1.0
	v_rcp_f32_e32 v54, v53
	v_pk_mul_f32 v[46:47], v[46:47], v[68:69] op_sel_hi:[1,0]
	v_cvt_pk_bf16_f32 v44, v44, v45
	v_cvt_pk_bf16_f32 v45, v46, v47
	global_store_dwordx2 v[64:65], v[44:45], off offset:96
	v_fma_f32 v44, -v53, v54, 1.0
	v_fmac_f32_e32 v54, v44, v54
	v_div_scale_f32 v44, vcc, 1.0, v52, 1.0
	v_mul_f32_e32 v45, v44, v54
	v_fma_f32 v46, -v53, v45, v44
	v_fmac_f32_e32 v45, v46, v54
	v_fma_f32 v44, -v53, v45, v44
	v_div_fmas_f32 v44, v44, v54, v45
	v_div_fixup_f32 v44, v44, v52, 1.0
	v_pk_mul_f32 v[40:41], v[40:41], v[44:45] op_sel_hi:[1,0]
	v_pk_mul_f32 v[42:43], v[42:43], v[44:45] op_sel_hi:[1,0]
	v_cvt_pk_bf16_f32 v40, v40, v41
	v_cvt_pk_bf16_f32 v41, v42, v43
	ds_bpermute_b32 v42, v233, v157
	v_lshlrev_b64 v[46:47], 11, v[150:151]
	v_lshl_add_u64 v[46:47], v[66:67], 0, v[46:47]
	global_store_dwordx2 v[46:47], v[40:41], off offset:32
	v_pk_mul_f32 v[36:37], v[36:37], v[44:45] op_sel_hi:[1,0]
	s_waitcnt lgkmcnt(0)
	v_add_f32_e32 v40, v157, v42
	ds_bpermute_b32 v41, v234, v40
	v_pk_mul_f32 v[38:39], v[38:39], v[44:45] op_sel_hi:[1,0]
	v_cvt_pk_bf16_f32 v36, v36, v37
	v_cvt_pk_bf16_f32 v37, v38, v39
	global_store_dwordx2 v[46:47], v[36:37], off offset:64
	s_waitcnt lgkmcnt(0)
	v_add_f32_e32 v36, v40, v41
	v_div_scale_f32 v37, s[0:1], v36, v36, 1.0
	v_rcp_f32_e32 v38, v37
	v_pk_mul_f32 v[28:29], v[28:29], v[44:45] op_sel_hi:[1,0]
	v_pk_mul_f32 v[30:31], v[30:31], v[44:45] op_sel_hi:[1,0]
	v_cvt_pk_bf16_f32 v28, v28, v29
	v_cvt_pk_bf16_f32 v29, v30, v31
	global_store_dwordx2 v[46:47], v[28:29], off offset:96
	v_fma_f32 v28, -v37, v38, 1.0
	v_fmac_f32_e32 v38, v28, v38
	v_div_scale_f32 v28, vcc, 1.0, v36, 1.0
	v_mul_f32_e32 v29, v28, v38
	v_fma_f32 v30, -v37, v29, v28
	v_fmac_f32_e32 v29, v30, v38
	v_fma_f32 v28, -v37, v29, v28
	v_div_fmas_f32 v28, v28, v38, v29
	v_div_fixup_f32 v28, v28, v36, 1.0
	v_pk_mul_f32 v[24:25], v[24:25], v[28:29] op_sel_hi:[1,0]
	v_pk_mul_f32 v[26:27], v[26:27], v[28:29] op_sel_hi:[1,0]
	v_cvt_pk_bf16_f32 v24, v24, v25
	v_cvt_pk_bf16_f32 v25, v26, v27
	ds_bpermute_b32 v26, v233, v156
	v_lshlrev_b64 v[30:31], 11, v[148:149]
	v_lshl_add_u64 v[30:31], v[66:67], 0, v[30:31]
	global_store_dwordx2 v[30:31], v[24:25], off offset:32
	v_pk_mul_f32 v[20:21], v[20:21], v[28:29] op_sel_hi:[1,0]
	s_waitcnt lgkmcnt(0)
	v_add_f32_e32 v24, v156, v26
	ds_bpermute_b32 v25, v234, v24
	v_pk_mul_f32 v[22:23], v[22:23], v[28:29] op_sel_hi:[1,0]
	v_cvt_pk_bf16_f32 v20, v20, v21
	v_cvt_pk_bf16_f32 v21, v22, v23
	global_store_dwordx2 v[30:31], v[20:21], off offset:64
	s_waitcnt lgkmcnt(0)
	v_add_f32_e32 v20, v24, v25
	v_div_scale_f32 v21, s[0:1], v20, v20, 1.0
	v_rcp_f32_e32 v22, v21
	v_pk_mul_f32 v[12:13], v[12:13], v[28:29] op_sel_hi:[1,0]
	v_pk_mul_f32 v[14:15], v[14:15], v[28:29] op_sel_hi:[1,0]
	v_cvt_pk_bf16_f32 v12, v12, v13
	v_cvt_pk_bf16_f32 v13, v14, v15
	global_store_dwordx2 v[30:31], v[12:13], off offset:96
	v_fma_f32 v12, -v21, v22, 1.0
	v_fmac_f32_e32 v22, v12, v22
	v_div_scale_f32 v12, vcc, 1.0, v20, 1.0
	v_mul_f32_e32 v13, v12, v22
	v_fma_f32 v14, -v21, v13, v12
	v_fmac_f32_e32 v13, v14, v22
	v_fma_f32 v12, -v21, v13, v12
	v_div_fmas_f32 v12, v12, v22, v13
	v_div_fixup_f32 v12, v12, v20, 1.0
	v_pk_mul_f32 v[60:61], v[60:61], v[68:69] op_sel_hi:[1,0]
	v_pk_mul_f32 v[62:63], v[62:63], v[68:69] op_sel_hi:[1,0]
	v_pk_mul_f32 v[48:49], v[48:49], v[44:45] op_sel_hi:[1,0]
	v_pk_mul_f32 v[50:51], v[50:51], v[44:45] op_sel_hi:[1,0]
	v_pk_mul_f32 v[32:33], v[32:33], v[28:29] op_sel_hi:[1,0]
	v_pk_mul_f32 v[34:35], v[34:35], v[28:29] op_sel_hi:[1,0]
	v_lshlrev_b64 v[14:15], 11, v[146:147]
	v_pk_mul_f32 v[16:17], v[16:17], v[12:13] op_sel_hi:[1,0]
	v_pk_mul_f32 v[18:19], v[18:19], v[12:13] op_sel_hi:[1,0]
	v_pk_mul_f32 v[8:9], v[8:9], v[12:13] op_sel_hi:[1,0]
	v_pk_mul_f32 v[10:11], v[10:11], v[12:13] op_sel_hi:[1,0]
	v_pk_mul_f32 v[4:5], v[4:5], v[12:13] op_sel_hi:[1,0]
	v_pk_mul_f32 v[6:7], v[6:7], v[12:13] op_sel_hi:[1,0]
	v_pk_mul_f32 v[0:1], v[0:1], v[12:13] op_sel_hi:[1,0]
	v_pk_mul_f32 v[2:3], v[2:3], v[12:13] op_sel_hi:[1,0]
	v_cvt_pk_bf16_f32 v60, v60, v61
	v_cvt_pk_bf16_f32 v61, v62, v63
	v_cvt_pk_bf16_f32 v48, v48, v49
	v_cvt_pk_bf16_f32 v49, v50, v51
	v_cvt_pk_bf16_f32 v32, v32, v33
	v_cvt_pk_bf16_f32 v33, v34, v35
	v_lshl_add_u64 v[14:15], v[66:67], 0, v[14:15]
	v_cvt_pk_bf16_f32 v16, v16, v17
	v_cvt_pk_bf16_f32 v17, v18, v19
	v_cvt_pk_bf16_f32 v8, v8, v9
	v_cvt_pk_bf16_f32 v9, v10, v11
	v_cvt_pk_bf16_f32 v4, v4, v5
	v_cvt_pk_bf16_f32 v5, v6, v7
	v_cvt_pk_bf16_f32 v0, v0, v1
	v_cvt_pk_bf16_f32 v1, v2, v3
	global_store_dwordx2 v[64:65], v[60:61], off
	global_store_dwordx2 v[46:47], v[48:49], off
	global_store_dwordx2 v[30:31], v[32:33], off
	global_store_dwordx2 v[14:15], v[16:17], off
	global_store_dwordx2 v[14:15], v[8:9], off offset:32
	global_store_dwordx2 v[14:15], v[4:5], off offset:64
	global_store_dwordx2 v[14:15], v[0:1], off offset:96
	v_mov_b32_e32 v245, 0x20010
	v_mov_b32_e32 v244, 1
	s_mov_b64 s[98:99], exec
	s_mov_b64 exec, 1
	ds_add_rtn_u32 v243, v245, v244
	s_waitcnt lgkmcnt(0)
	s_mov_b64 exec, s[98:99]
	s_nop 1
	v_readfirstlane_b32 s3, v243
	s_lshl_b32 s100, s2, 3
	s_and_b32 s101, s3, 7
	s_lshr_b32 s3, s3, 3
	s_lshl_b32 s3, s3, 11
	s_add_i32 s3, s3, s101
	s_add_i32 s3, s3, s100
	s_cmpk_lt_i32 s3, 0x2000
	s_cbranch_scc1 .LBB0_231
